# NA window blocks: bias-table LDS reads of a block issued together instead of one at a time
# speedup vs baseline: 1.0161x; 1.0030x over previous
; __device__ __forceinline__ void na_task(const P& p, int task, int lane, float* ldsw  ) {
;     ...
;         auto ldk = [&](int i, AttnKn& k) {
;             const bf16_t* k0p = (i < 16) ? kbase + ((size_t)b * TLAT + (r0 + (i >> 1)) * 64 + (i & 1) * 32 + fr) * 1024 : kbase + ((size_t)MLAT + b * TCTX + (i - 16) * 32 + fr) * 1024;
;             k.a00 = *(const bf16x8*)k0p; k.a01 = *(const bf16x8*)(k0p + 32); k.a10 = *(const bf16x8*)(k0p + 16 * 1024); k.a11 = *(const bf16x8*)(k0p + 16 * 1024 + 32);
;         };
;         auto ldv = [&](int i, AttnVn& v) {
;             const int tok0 = (i < 16) ? (r0 + (i >> 1)) * 64 + (i & 1) * 32 : TLAT + (i - 16) * 32;
; #pragma unroll
;             for (int dt = 0; dt < 4; ++dt) { const bf16_t* vp = vb + (size_t)(dt * 16 + fr) * TT + tok0 + 4 * g; v.va[dt][0] = *(const s16x4*)vp; v.va[dt][1] = *(const s16x4*)(vp + 16); }
;         };
;         asm volatile("s_waitcnt lgkmcnt(0)" ::: "memory");
;         AttnKn kc, kn; AttnVn vv; ldk(0, kc);
; #pragma unroll 1
;         for (int i = 0; i < 24; ++i) {
;             ldk(i + 1 < 24 ? i + 1 : i, kn);
;             ldv(i, vv);
;             const int half = i & 1;
;             const float* rp = ldsw + (r0 + (i >> 1) - r + 7) * 31;
; #pragma unroll
;             for (int j = 0; j < 4; ++j) {
;                 if (i < 16 && (half ? j == 0 : j == 3)) continue;
;                 float mbv[8];
;                 if (i < 16) {
;                     const int qcol = j * 16 + fr, cst = clampi(qcol - 8, 0, 48);
; #pragma unroll
;                     for (int q8 = 0; q8 < 8; ++q8) { const int kk = (q8 < 4) ? 4 * g + q8 : 12 + 4 * g + q8; const int kcc = half * 32 + kk;
;                         const bool ok = (kcc >= cst) && (kcc < cst + 16); const float bv = rp[clampi(kcc - qcol + 15, 0, 30)]; mbv[q8] = ok ? bv : -2e30f; }
.LBB0_398:
	v_ashrrev_i32_e32 v99, 31, v98
	v_lshlrev_b64 v[98:99], 1, v[98:99]
	v_lshl_add_u64 v[100:101], v[158:159], 0, v[98:99]
	v_lshl_add_u64 v[102:103], v[160:161], 0, v[98:99]
	global_load_dwordx2 v[110:111], v[100:101], off
	global_load_dwordx2 v[112:113], v[100:101], off offset:32
	global_load_dwordx2 v[106:107], v[102:103], off
	global_load_dwordx2 v[108:109], v[102:103], off offset:32
	v_lshl_add_u64 v[100:101], v[162:163], 0, v[98:99]
	v_lshl_add_u64 v[202:203], v[164:165], 0, v[98:99]
	global_load_dwordx2 v[102:103], v[100:101], off
	global_load_dwordx2 v[104:105], v[100:101], off offset:32
	global_load_dwordx2 v[98:99], v[202:203], off
	s_nop 0
	global_load_dwordx2 v[100:101], v[202:203], off offset:32
	s_and_b32 s54, s48, 1
	v_add_u32_e32 v0, s49, v149
	s_movk_i32 s44, 0x7c
	s_cmp_eq_u32 s54, 0
	v_mul_lo_u32 v0, v0, s44
	s_cselect_b64 s[48:49], -1, 0
	s_cmp_eq_u32 s54, 1
	v_cndmask_b32_e64 v202, 0, 1, s[46:47]
	s_cselect_b64 s[82:83], -1, 0
	v_cmp_ne_u32_e64 s[44:45], 1, v202
	s_andn2_b64 vcc, exec, s[46:47]
	v_add_u32_e32 v219, s85, v0
	s_cbranch_vccnz .LBB0_401
	s_and_b64 vcc, exec, s[48:49]
	s_cbranch_vccz .LBB0_402
	v_lshl_add_u32 v204, v145, 2, v219
	v_lshl_add_u32 v0, v124, 2, v204
	ds_read2_b32 v[202:203], v0 offset0:217 offset1:218
	v_lshl_add_u32 v205, v169, 2, v204
	ds_read2_b32 v[204:205], v205 offset0:217 offset1:218
	v_lshl_add_u32 v224, v171, 2, v219
	ds_read_b32 v224, v224 offset:928
	v_lshl_add_u32 v225, v173, 2, v219
	ds_read_b32 v225, v225 offset:928
	v_lshl_add_u32 v226, v175, 2, v219
	ds_read_b32 v226, v226 offset:928
	v_lshl_add_u32 v227, v177, 2, v219
	ds_read_b32 v227, v227 offset:928
	s_waitcnt lgkmcnt(0)
	v_cndmask_b32_e64 v220, v202, v200, s[8:9]
	v_cndmask_b32_e64 v0, v203, v200, s[6:7]
	v_cndmask_b32_e64 v223, v204, v200, s[12:13]
	v_cndmask_b32_e64 v222, v205, v200, s[10:11]
	v_cndmask_b32_e64 v224, v200, v224, s[14:15]
	v_cndmask_b32_e64 v225, v200, v225, s[16:17]
	v_cndmask_b32_e64 v226, v200, v226, s[18:19]
	v_cndmask_b32_e64 v227, v200, v227, s[20:21]
	s_cbranch_execnz .LBB0_404
	s_branch .LBB0_405

; __device__ __forceinline__ unsigned pk2(float lo, float hi) { unsigned r; asm("v_cvt_pk_bf16_f32 %0, %1, %2" : "=v"(r) : "v"(lo), "v"(hi)); return r; }
; __device__ __forceinline__ float xmax32(float x) { unsigned a = __builtin_bit_cast(unsigned, x), b = a; asm volatile("" : "+v"(b)); auto r = __builtin_amdgcn_permlane32_swap(a, b, false, false); return fmaxf(__builtin_bit_cast(float, (unsigned)r[0]), __builtin_bit_cast(float, (unsigned)r[1])); }
; template <class KV>
; __device__ __forceinline__ void attn_compute(const KV& kv, const float (&mbv)[8], bf16x8 q0, bf16x8 q1, AttnState& st) {
;     f32x4 s0 = {0.f, 0.f, 0.f, 0.f}, s1 = {0.f, 0.f, 0.f, 0.f};
;     s0 = mfma16(kv.a00, q0, s0); s0 = mfma16(kv.a01, q1, s0); s1 = mfma16(kv.a10, q0, s1); s1 = mfma16(kv.a11, q1, s1);
;     float sc[8];
; #pragma unroll
;     for (int r = 0; r < 4; ++r) { sc[r] = s0[r] * 0.125f + mbv[r]; sc[4 + r] = s1[r] * 0.125f + mbv[4 + r]; }
;     float mx = sc[0];
; #pragma unroll
;     for (int i = 1; i < 8; ++i) mx = fmaxf(mx, sc[i]);
;     mx = xmax16(xmax32(mx));
;     const float mn = fmaxf(st.m, mx), corr = __expf(st.m - mn); st.m = mn;
;     float pp[8], ps = 0.f;
; #pragma unroll
;     for (int i = 0; i < 8; ++i) { pp[i] = __expf(sc[i] - mn); ps += pp[i]; }
;     st.l = st.l * corr + ps;
;     u32x4 pw; pw.x = pk2(pp[0], pp[1]); pw.y = pk2(pp[2], pp[3]); pw.z = pk2(pp[4], pp[5]); pw.w = pk2(pp[6], pp[7]);
;     const bf16x8 pb = __builtin_bit_cast(bf16x8, pw);
; #pragma unroll
;     for (int dt = 0; dt < 4; ++dt) {
;         bf16x8 v8; v8[0] = kv.va[dt][0][0]; v8[1] = kv.va[dt][0][1]; v8[2] = kv.va[dt][0][2]; v8[3] = kv.va[dt][0][3]; v8[4] = kv.va[dt][1][0]; v8[5] = kv.va[dt][1][1]; v8[6] = kv.va[dt][1][2]; v8[7] = kv.va[dt][1][3];
;         st.o[dt] = mfma16(v8, pb, st.o[dt] * corr);
;     }
; }
; __device__ __forceinline__ void na_task(const P& p, int task, int lane, float* ldsw  ) {
;     ...
;                 if (i < 16) {
;                     const int qcol = j * 16 + fr, cst = clampi(qcol - 8, 0, 48);
; #pragma unroll
;                     for (int q8 = 0; q8 < 8; ++q8) { const int kk = (q8 < 4) ? 4 * g + q8 : 12 + 4 * g + q8; const int kcc = half * 32 + kk;
;                         const bool ok = (kcc >= cst) && (kcc < cst + 16); const float bv = rp[clampi(kcc - qcol + 15, 0, 30)]; mbv[q8] = ok ? bv : -2e30f; }
.LBB0_407:
	ds_read_b128 v[242:245], v143 offset:4352
	ds_read_b128 v[246:249], v143 offset:4416
	s_waitcnt vmcnt(15) lgkmcnt(1)
	v_mfma_f32_16x16x32_bf16 v[202:205], v[78:81], v[242:245], 0
	s_waitcnt vmcnt(13)
	v_mfma_f32_16x16x32_bf16 v[242:245], v[74:77], v[242:245], 0
	s_waitcnt lgkmcnt(0)
	v_mfma_f32_16x16x32_bf16 v[202:205], v[70:73], v[246:249], v[202:205]
	s_waitcnt vmcnt(12)
	v_mfma_f32_16x16x32_bf16 v[242:245], v[66:69], v[246:249], v[242:245]
	s_nop 5
	v_fmac_f32_e32 v224, 0x3e000000, v202
	v_fmac_f32_e32 v222, 0x3e000000, v203
	v_fmac_f32_e32 v223, 0x3e000000, v204
	v_fmac_f32_e32 v0, 0x3e000000, v205
	v_max_f32_e32 v202, v224, v222
	v_fmac_f32_e32 v225, 0x3e000000, v242
	v_fmac_f32_e32 v226, 0x3e000000, v243
	v_max3_f32 v202, v202, v223, v0
	v_fmac_f32_e32 v227, 0x3e000000, v244
	v_fmac_f32_e32 v228, 0x3e000000, v245
	v_max3_f32 v202, v202, v225, v226
	v_max3_f32 v202, v202, v227, v228
	v_mov_b32_e32 v203, v202
	s_nop 1
	v_permlane32_swap_b32_e32 v202, v203
	v_max_f32_e32 v203, v203, v203
	v_max_f32_e32 v202, v202, v202
	v_max_f32_e32 v202, v202, v203
	v_mov_b32_e32 v203, v202
	s_nop 1
	v_permlane16_swap_b32_e32 v202, v203
	v_max3_f32 v220, v221, v202, v203
	v_sub_f32_e32 v0, v0, v220
	v_mul_f32_e32 v0, 0x3fb8aa3b, v0
	v_sub_f32_e32 v203, v224, v220
	v_exp_f32_e32 v224, v0
	v_sub_f32_e32 v0, v225, v220
	v_mul_f32_e32 v0, 0x3fb8aa3b, v0
	v_exp_f32_e32 v225, v0
	v_sub_f32_e32 v0, v226, v220
	v_mul_f32_e32 v0, 0x3fb8aa3b, v0
	v_exp_f32_e32 v226, v0
	v_sub_f32_e32 v0, v227, v220
	v_mul_f32_e32 v0, 0x3fb8aa3b, v0
	v_sub_f32_e32 v202, v221, v220
	v_exp_f32_e32 v227, v0
	v_sub_f32_e32 v0, v228, v220
	v_mul_f32_e32 v202, 0x3fb8aa3b, v202
	v_mul_f32_e32 v0, 0x3fb8aa3b, v0
	v_mul_f32_e32 v203, 0x3fb8aa3b, v203
	v_exp_f32_e32 v228, v0
	v_exp_f32_e32 v0, v202
	v_exp_f32_e32 v221, v203
	v_sub_f32_e32 v203, v222, v220
	v_mul_f32_e32 v203, 0x3fb8aa3b, v203
	v_exp_f32_e32 v222, v203
	v_sub_f32_e32 v203, v223, v220
	v_mul_f32_e32 v203, 0x3fb8aa3b, v203
	v_pk_mul_f32 v[52:53], v[52:53], v[0:1] op_sel_hi:[1,0]
	v_pk_mul_f32 v[50:51], v[50:51], v[0:1] op_sel_hi:[1,0]
	v_pk_mul_f32 v[44:45], v[44:45], v[0:1] op_sel_hi:[1,0]
	v_pk_mul_f32 v[42:43], v[42:43], v[0:1] op_sel_hi:[1,0]
	v_pk_mul_f32 v[40:41], v[40:41], v[0:1] op_sel_hi:[1,0]
	v_pk_mul_f32 v[38:39], v[38:39], v[0:1] op_sel_hi:[1,0]
	v_pk_mul_f32 v[36:37], v[36:37], v[0:1] op_sel_hi:[1,0]
	v_pk_mul_f32 v[34:35], v[34:35], v[0:1] op_sel_hi:[1,0]
	v_exp_f32_e32 v223, v203
	v_cvt_pk_bf16_f32 v202, v221, v222
	v_cvt_pk_bf16_f32 v203, v223, v224
	v_cvt_pk_bf16_f32 v204, v225, v226
	v_cvt_pk_bf16_f32 v205, v227, v228
	s_waitcnt vmcnt(6)
	v_mfma_f32_16x16x32_bf16 v[50:53], v[110:113], v[202:205], v[50:53]
	s_waitcnt vmcnt(4)
	v_mfma_f32_16x16x32_bf16 v[42:45], v[106:109], v[202:205], v[42:45]
	s_waitcnt vmcnt(2)
	v_mfma_f32_16x16x32_bf16 v[38:41], v[102:105], v[202:205], v[38:41]
	s_waitcnt vmcnt(0)
	v_mfma_f32_16x16x32_bf16 v[34:37], v[98:101], v[202:205], v[34:37]
	s_and_b64 vcc, exec, s[44:45]
	v_mov_b32_e32 v243, 0
	v_mov_b32_e32 v242, 0
	v_mov_b32_e32 v241, 0
	v_mov_b32_e32 v239, 0
	v_mov_b32_e32 v238, 0
	v_mov_b32_e32 v235, 0
	v_mov_b32_e32 v233, 0
	s_cbranch_vccnz .LBB0_409
	v_sub_u32_e32 v233, v240, v181
	v_add_u32_e32 v202, 15, v233
	v_min_u32_e32 v202, 30, v202
	v_cmp_lt_i32_e64 s[46:47], -16, v233
	s_nop 1
	v_cndmask_b32_e64 v233, 0, v202, s[46:47]
	v_lshl_add_u32 v233, v233, 2, v219
	ds_read_b32 v233, v233 offset:868
	v_sub_u32_e32 v235, v236, v181
	v_add_u32_e32 v202, 15, v235
	v_min_u32_e32 v202, 30, v202
	v_cmp_lt_i32_e64 s[46:47], -16, v235
	s_nop 1
	v_cndmask_b32_e64 v235, 0, v202, s[46:47]
	v_lshl_add_u32 v235, v235, 2, v219
	ds_read_b32 v235, v235 offset:868
	v_sub_u32_e32 v238, v234, v181
	v_add_u32_e32 v202, 15, v238
	v_min_u32_e32 v202, 30, v202
	v_cmp_lt_i32_e64 s[46:47], -16, v238
	s_nop 1
	v_cndmask_b32_e64 v238, 0, v202, s[46:47]
	v_lshl_add_u32 v238, v238, 2, v219
	ds_read_b32 v238, v238 offset:868
	v_sub_u32_e32 v239, v232, v181
	v_add_u32_e32 v202, 15, v239
	v_min_u32_e32 v202, 30, v202
	v_cmp_lt_i32_e64 s[46:47], -16, v239
	s_nop 1
	v_cndmask_b32_e64 v239, 0, v202, s[46:47]
	v_lshl_add_u32 v239, v239, 2, v219
	ds_read_b32 v239, v239 offset:868
	v_or_b32_e32 v203, s54, v170
	v_sub_u32_e32 v241, v203, v181
	v_add_u32_e32 v202, 15, v241
	v_min_u32_e32 v202, 30, v202
	v_cmp_lt_i32_e64 s[46:47], -16, v241
	s_nop 1
	v_cndmask_b32_e64 v241, 0, v202, s[46:47]
	v_lshl_add_u32 v241, v241, 2, v219
	ds_read_b32 v241, v241 offset:868
	v_sub_u32_e32 v242, v231, v181
	v_add_u32_e32 v202, 15, v242
	v_min_u32_e32 v202, 30, v202
	v_cmp_lt_i32_e64 s[46:47], -16, v242
	s_nop 1
	v_cndmask_b32_e64 v242, 0, v202, s[46:47]
	v_lshl_add_u32 v242, v242, 2, v219
	ds_read_b32 v242, v242 offset:868
	v_sub_u32_e32 v243, v230, v181
	v_add_u32_e32 v202, 15, v243
	v_min_u32_e32 v202, 30, v202
	v_cmp_lt_i32_e64 s[46:47], -16, v243
	s_nop 1
	v_cndmask_b32_e64 v243, 0, v202, s[46:47]
	v_lshl_add_u32 v243, v243, 2, v219
	ds_read_b32 v243, v243 offset:868
	v_sub_u32_e32 v237, v229, v181
	v_add_u32_e32 v202, 15, v237
	v_min_u32_e32 v202, 30, v202
	v_cmp_lt_i32_e64 s[46:47], -16, v237
	s_nop 1
	v_cndmask_b32_e64 v237, 0, v202, s[46:47]
	v_lshl_add_u32 v237, v237, 2, v219
	ds_read_b32 v237, v237 offset:868
	s_waitcnt lgkmcnt(0)
	v_cmp_ge_u32_e32 vcc, v240, v180
	v_cmp_lt_u32_e64 s[46:47], v240, v182
	s_and_b64 vcc, vcc, s[46:47]
	s_nop 0
	v_cndmask_b32_e32 v233, v200, v233, vcc
	v_cmp_ge_u32_e32 vcc, v236, v180
	v_cmp_lt_u32_e64 s[46:47], v236, v182
	s_and_b64 vcc, vcc, s[46:47]
	s_nop 0
	v_cndmask_b32_e32 v235, v200, v235, vcc
	v_cmp_ge_u32_e32 vcc, v234, v180
	v_cmp_lt_u32_e64 s[46:47], v234, v182
	s_and_b64 vcc, vcc, s[46:47]
	s_nop 0
	v_cndmask_b32_e32 v238, v200, v238, vcc
	v_cmp_ge_u32_e32 vcc, v232, v180
	v_cmp_lt_u32_e64 s[46:47], v232, v182
	s_and_b64 vcc, vcc, s[46:47]
	s_nop 0
	v_cndmask_b32_e32 v239, v200, v239, vcc
	v_or_b32_e32 v203, s54, v170
	v_cmp_ge_u32_e32 vcc, v203, v180
	v_cmp_lt_u32_e64 s[46:47], v203, v182
	s_and_b64 vcc, vcc, s[46:47]
	s_nop 0
	v_cndmask_b32_e32 v241, v200, v241, vcc
	v_cmp_ge_u32_e32 vcc, v231, v180
	v_cmp_lt_u32_e64 s[46:47], v231, v182
	s_and_b64 vcc, vcc, s[46:47]
	s_nop 0
	v_cndmask_b32_e32 v242, v200, v242, vcc
	v_cmp_ge_u32_e32 vcc, v230, v180
	v_cmp_lt_u32_e64 s[46:47], v230, v182
	s_and_b64 vcc, vcc, s[46:47]
	s_nop 0
	v_cndmask_b32_e32 v243, v200, v243, vcc
	v_cmp_ge_u32_e32 vcc, v229, v180
	v_cmp_lt_u32_e64 s[46:47], v229, v182
	s_and_b64 vcc, vcc, s[46:47]
	s_nop 0
	v_cndmask_b32_e32 v237, v200, v237, vcc
; __device__ __forceinline__ unsigned pk2(float lo, float hi) { unsigned r; asm("v_cvt_pk_bf16_f32 %0, %1, %2" : "=v"(r) : "v"(lo), "v"(hi)); return r; }
; __device__ __forceinline__ float xmax32(float x) { unsigned a = __builtin_bit_cast(unsigned, x), b = a; asm volatile("" : "+v"(b)); auto r = __builtin_amdgcn_permlane32_swap(a, b, false, false); return fmaxf(__builtin_bit_cast(float, (unsigned)r[0]), __builtin_bit_cast(float, (unsigned)r[1])); }
; template <class KV>
; __device__ __forceinline__ void attn_compute(const KV& kv, const float (&mbv)[8], bf16x8 q0, bf16x8 q1, AttnState& st) {
;     f32x4 s0 = {0.f, 0.f, 0.f, 0.f}, s1 = {0.f, 0.f, 0.f, 0.f};
;     s0 = mfma16(kv.a00, q0, s0); s0 = mfma16(kv.a01, q1, s0); s1 = mfma16(kv.a10, q0, s1); s1 = mfma16(kv.a11, q1, s1);
;     float sc[8];
; #pragma unroll
;     for (int r = 0; r < 4; ++r) { sc[r] = s0[r] * 0.125f + mbv[r]; sc[4 + r] = s1[r] * 0.125f + mbv[4 + r]; }
;     float mx = sc[0];
; #pragma unroll
;     for (int i = 1; i < 8; ++i) mx = fmaxf(mx, sc[i]);
;     mx = xmax16(xmax32(mx));
;     const float mn = fmaxf(st.m, mx), corr = __expf(st.m - mn); st.m = mn;
;     float pp[8], ps = 0.f;
; #pragma unroll
;     for (int i = 0; i < 8; ++i) { pp[i] = __expf(sc[i] - mn); ps += pp[i]; }
;     st.l = st.l * corr + ps;
;     u32x4 pw; pw.x = pk2(pp[0], pp[1]); pw.y = pk2(pp[2], pp[3]); pw.z = pk2(pp[4], pp[5]); pw.w = pk2(pp[6], pp[7]);
;     const bf16x8 pb = __builtin_bit_cast(bf16x8, pw);
; #pragma unroll
;     for (int dt = 0; dt < 4; ++dt) {
;         bf16x8 v8; v8[0] = kv.va[dt][0][0]; v8[1] = kv.va[dt][0][1]; v8[2] = kv.va[dt][0][2]; v8[3] = kv.va[dt][0][3]; v8[4] = kv.va[dt][1][0]; v8[5] = kv.va[dt][1][1]; v8[6] = kv.va[dt][1][2]; v8[7] = kv.va[dt][1][3];
;         st.o[dt] = mfma16(v8, pb, st.o[dt] * corr);
;     }
; }
; __device__ __forceinline__ void na_task(const P& p, int task, int lane, float* ldsw  ) {
;     ...
;                 if (i < 16) {
;                     const int qcol = j * 16 + fr, cst = clampi(qcol - 8, 0, 48);
; #pragma unroll
;                     for (int q8 = 0; q8 < 8; ++q8) { const int kk = (q8 < 4) ? 4 * g + q8 : 12 + 4 * g + q8; const int kcc = half * 32 + kk;
;                         const bool ok = (kcc >= cst) && (kcc < cst + 16); const float bv = rp[clampi(kcc - qcol + 15, 0, 30)]; mbv[q8] = ok ? bv : -2e30f; }
.LBB0_409:
	ds_read_b128 v[202:205], v143 offset:6656
	ds_read_b128 v[244:247], v143 offset:6720
	s_waitcnt lgkmcnt(1)
	v_mfma_f32_16x16x32_bf16 v[248:251], v[78:81], v[202:205], 0
	v_mfma_f32_16x16x32_bf16 v[202:205], v[74:77], v[202:205], 0
	s_waitcnt lgkmcnt(0)
	v_mfma_f32_16x16x32_bf16 v[248:251], v[70:73], v[244:247], v[248:251]
	v_mfma_f32_16x16x32_bf16 v[202:205], v[66:69], v[244:247], v[202:205]
	s_nop 6
	v_fmac_f32_e32 v233, 0x3e000000, v248
	v_fmac_f32_e32 v235, 0x3e000000, v249
	v_fmac_f32_e32 v241, 0x3e000000, v202
	v_fmac_f32_e32 v238, 0x3e000000, v250
	v_fmac_f32_e32 v239, 0x3e000000, v251
	v_max_f32_e32 v202, v233, v235
	v_fmac_f32_e32 v242, 0x3e000000, v203
	v_max3_f32 v202, v202, v238, v239
	v_fmac_f32_e32 v243, 0x3e000000, v204
	v_fmac_f32_e32 v237, 0x3e000000, v205
	v_max3_f32 v202, v202, v241, v242
	v_max3_f32 v202, v202, v243, v237
	v_mov_b32_e32 v203, v202
	s_nop 1
	v_permlane32_swap_b32_e32 v202, v203
	v_max_f32_e32 v203, v203, v203
	v_max_f32_e32 v202, v202, v202
	v_max_f32_e32 v202, v202, v203
	v_mov_b32_e32 v203, v202
	s_nop 1
	v_permlane16_swap_b32_e32 v202, v203
	v_max3_f32 v229, v166, v202, v203
	v_sub_f32_e32 v202, v233, v229
	v_mul_f32_e32 v202, 0x3fb8aa3b, v202
	v_exp_f32_e32 v230, v202
	v_sub_f32_e32 v202, v235, v229
	v_mul_f32_e32 v202, 0x3fb8aa3b, v202
	v_exp_f32_e32 v231, v202
	v_sub_f32_e32 v202, v238, v229
	v_mul_f32_e32 v202, 0x3fb8aa3b, v202
	v_exp_f32_e32 v232, v202
	v_sub_f32_e32 v202, v239, v229
	v_mul_f32_e32 v202, 0x3fb8aa3b, v202
	v_exp_f32_e32 v233, v202
	v_sub_f32_e32 v202, v241, v229
	v_sub_f32_e32 v166, v166, v229
	v_mul_f32_e32 v202, 0x3fb8aa3b, v202
	v_mul_f32_e32 v166, 0x3fb8aa3b, v166
	v_exp_f32_e32 v234, v202
	v_sub_f32_e32 v202, v242, v229
	v_mul_f32_e32 v202, 0x3fb8aa3b, v202
	v_exp_f32_e32 v166, v166
	v_exp_f32_e32 v235, v202
	v_sub_f32_e32 v202, v243, v229
	v_mul_f32_e32 v202, 0x3fb8aa3b, v202
	v_exp_f32_e32 v236, v202
	v_sub_f32_e32 v202, v237, v229
	v_mul_f32_e32 v202, 0x3fb8aa3b, v202
	v_pk_mul_f32 v[32:33], v[32:33], v[166:167] op_sel_hi:[1,0]
	v_pk_mul_f32 v[30:31], v[30:31], v[166:167] op_sel_hi:[1,0]
	v_pk_mul_f32 v[28:29], v[28:29], v[166:167] op_sel_hi:[1,0]
	v_pk_mul_f32 v[26:27], v[26:27], v[166:167] op_sel_hi:[1,0]
	v_pk_mul_f32 v[24:25], v[24:25], v[166:167] op_sel_hi:[1,0]
	v_pk_mul_f32 v[22:23], v[22:23], v[166:167] op_sel_hi:[1,0]
	v_pk_mul_f32 v[20:21], v[20:21], v[166:167] op_sel_hi:[1,0]
	v_pk_mul_f32 v[18:19], v[18:19], v[166:167] op_sel_hi:[1,0]
	v_exp_f32_e32 v237, v202
	v_cvt_pk_bf16_f32 v202, v230, v231
	v_cvt_pk_bf16_f32 v203, v232, v233
	v_cvt_pk_bf16_f32 v204, v234, v235
	v_cvt_pk_bf16_f32 v205, v236, v237
	s_nop 0
	v_mfma_f32_16x16x32_bf16 v[30:33], v[110:113], v[202:205], v[30:33]
	v_mfma_f32_16x16x32_bf16 v[26:29], v[106:109], v[202:205], v[26:29]
	v_mfma_f32_16x16x32_bf16 v[22:25], v[102:105], v[202:205], v[22:25]
	v_mfma_f32_16x16x32_bf16 v[18:21], v[98:101], v[202:205], v[18:21]
	s_and_b64 vcc, exec, s[44:45]
	s_cbranch_vccnz .LBB0_412
	s_and_b64 vcc, exec, s[82:83]
	s_cbranch_vccz .LBB0_413
	v_lshl_add_u32 v238, v183, 2, v219
	ds_read_b32 v238, v238 offset:868
	v_lshl_add_u32 v239, v207, 2, v219
	ds_read_b32 v239, v239 offset:868
	v_lshl_add_u32 v240, v208, 2, v219
	ds_read_b32 v240, v240 offset:868
	v_lshl_add_u32 v242, v209, 2, v219
	ds_read_b32 v242, v242 offset:868
	v_lshl_add_u32 v202, v210, 2, v219
	ds_read2_b32 v[202:203], v202 offset0:232 offset1:233
	v_lshl_add_u32 v204, v211, 2, v219
	ds_read2_b32 v[204:205], v204 offset0:232 offset1:233
	s_waitcnt lgkmcnt(0)
	v_cndmask_b32_e64 v238, v238, v200, s[22:23]
	v_cndmask_b32_e64 v239, v239, v200, s[24:25]
	v_cndmask_b32_e64 v240, v240, v200, s[26:27]
	v_cndmask_b32_e64 v242, v242, v200, s[28:29]
	v_cndmask_b32_e64 v243, v200, v202, s[34:35]
	v_cndmask_b32_e64 v241, v200, v203, s[30:31]
	v_cndmask_b32_e64 v244, v200, v204, s[42:43]
	v_cndmask_b32_e64 v219, v200, v205, s[40:41]
	s_cbranch_execnz .LBB0_415
	s_branch .LBB0_416

; __device__ __forceinline__ unsigned pk2(float lo, float hi) { unsigned r; asm("v_cvt_pk_bf16_f32 %0, %1, %2" : "=v"(r) : "v"(lo), "v"(hi)); return r; }
; __device__ __forceinline__ float siluf(float v) { return v * __builtin_amdgcn_rcpf(1.f + __expf(-v)); }
; __device__ __forceinline__ void dn_conv_token4(const P& p, int m0, int lane) {
;     const bf16_t* PRE = (const bf16_t*)(p.ws + WS_DNPRE);
;     int s0, s1;
;     if (m0 < MLAT) { s0 = m0 & ~2047; s1 = s0 + 2048; } else { s0 = MLAT + ((m0 - MLAT) & ~255); s1 = s0 + 256; }
; #pragma unroll 1
;     for (int cgp = 0; cgp < 3; ++cgp) {
;         const int col = cgp * 512 + lane * 8;
;         f32x4 w[5][2];
; #pragma unroll
;         for (int j = 0; j < 5; ++j) { w[j][0] = *(const f32x4*)(p.conv_w + j * 1536 + col); w[j][1] = *(const f32x4*)(p.conv_w + j * 1536 + col + 4); }
;         u32x4 xr[8];
; #pragma unroll
;         for (int r = 0; r < 8; ++r) { const int mm = m0 + r - 2; xr[r] = (mm >= s0 && mm < s1) ? *(const u32x4*)(PRE + (size_t)mm * 1536 + col) : (u32x4){0u, 0u, 0u, 0u}; }
;         bf16_t* dbase = (bf16_t*)(p.ws + (cgp == 0 ? WS_QN : (cgp == 1 ? WS_KN : WS_VV))) + lane * 8;
; #pragma unroll
;         for (int t = 0; t < 4; ++t) {
;             float acc[8];
; #pragma unroll
;             for (int i = 0; i < 8; ++i) acc[i] = 0.f;
; #pragma unroll
;             for (int j = 0; j < 5; ++j) { const u32x4 xv = xr[t + j];
;                 acc[0] += bflo(xv.x) * w[j][0][0]; acc[1] += bfhi(xv.x) * w[j][0][1]; acc[2] += bflo(xv.y) * w[j][0][2]; acc[3] += bfhi(xv.y) * w[j][0][3];
;                 acc[4] += bflo(xv.z) * w[j][1][0]; acc[5] += bfhi(xv.z) * w[j][1][1]; acc[6] += bflo(xv.w) * w[j][1][2]; acc[7] += bfhi(xv.w) * w[j][1][3]; }
;             float ss = 0.f;
; #pragma unroll
;             for (int i = 0; i < 8; ++i) { acc[i] = siluf(acc[i]); ss += acc[i] * acc[i]; }
;             if (cgp < 2) {
;                 ss += __shfl_xor(ss, 1); ss += __shfl_xor(ss, 2); ss += __shfl_xor(ss, 4); ss += __shfl_xor(ss, 8);
;                 const float rn = 1.0f / sqrtf(ss + EPS);
; #pragma unroll
;                 for (int i = 0; i < 8; ++i) acc[i] *= rn;
;             }
;             u32x4 o; o.x = pk2(acc[0], acc[1]); o.y = pk2(acc[2], acc[3]); o.z = pk2(acc[4], acc[5]); o.w = pk2(acc[6], acc[7]);
;             *(u32x4*)(dbase + (size_t)(m0 + t) * 512) = o;
;         }
.LBB0_422:
	s_mul_i32 s9, s15, 0xc00
	s_mul_hi_i32 s8, s15, 0xc00
	s_add_u32 s26, s13, s9
	s_addc_u32 s27, s14, s8
	s_mul_i32 s9, s20, 0xc00
	s_mul_hi_i32 s8, s20, 0xc00
	s_add_u32 s28, s13, s9
	s_addc_u32 s29, s14, s8
	s_mul_i32 s9, s21, 0xc00
	s_mul_hi_i32 s8, s21, 0xc00
	s_add_u32 s30, s13, s9
	s_addc_u32 s31, s14, s8
	s_mul_i32 s9, s12, 0xc00
	s_mul_hi_i32 s8, s12, 0xc00
	s_add_u32 s34, s13, s9
	s_addc_u32 s35, s14, s8
	s_and_b32 s8, s16, 0xfffff800
	s_and_b32 s10, s16, 0x7fffff00
	s_add_i32 s9, s8, 0x800
	s_add_i32 s11, s10, 0x100
	s_cmpk_lt_i32 s16, 0x4000
	s_cselect_b32 s50, s9, s11
	s_cselect_b32 s52, s8, s10
	s_add_i32 s10, s16, -2
	s_cmp_ge_i32 s10, s52
	s_cselect_b64 s[8:9], -1, 0
	s_cmp_lt_i32 s10, s50
	s_cselect_b64 s[10:11], -1, 0
	s_and_b64 s[40:41], s[8:9], s[10:11]
	s_add_i32 s10, s16, -1
	s_cmp_ge_i32 s10, s52
	s_cselect_b64 s[8:9], -1, 0
	s_cmp_lt_i32 s10, s50
	s_cselect_b64 s[10:11], -1, 0
	s_and_b64 s[42:43], s[8:9], s[10:11]
	s_cmp_ge_i32 s16, s52
	s_cselect_b64 s[8:9], -1, 0
	s_cmp_lt_i32 s16, s50
	s_cselect_b64 s[10:11], -1, 0
	s_and_b64 s[44:45], s[8:9], s[10:11]
	s_ashr_i32 s17, s16, 31
	s_or_b32 s8, s16, 1
	s_cmp_ge_i32 s8, s52
	s_cselect_b64 s[10:11], -1, 0
	s_cmp_lt_i32 s8, s50
	s_cselect_b64 s[46:47], -1, 0
	s_and_b64 s[46:47], s[10:11], s[46:47]
	s_ashr_i32 s9, s8, 31
	s_or_b32 s10, s16, 2
	s_cmp_ge_i32 s10, s52
	s_cselect_b64 s[48:49], -1, 0
	s_cmp_lt_i32 s10, s50
	s_cselect_b64 s[72:73], -1, 0
	s_and_b64 s[48:49], s[48:49], s[72:73]
	s_ashr_i32 s11, s10, 31
	s_or_b32 s72, s16, 3
	s_cmp_ge_i32 s72, s52
	s_cselect_b64 s[74:75], -1, 0
	s_cmp_lt_i32 s72, s50
	s_cselect_b64 s[76:77], -1, 0
	s_and_b64 s[76:77], s[74:75], s[76:77]
	s_ashr_i32 s73, s72, 31
	s_add_i32 s54, s16, 4
	s_cmp_ge_i32 s54, s52
	s_cselect_b64 s[74:75], -1, 0
	s_cmp_lt_i32 s54, s50
	s_cselect_b64 s[78:79], -1, 0
	s_and_b64 s[80:81], s[74:75], s[78:79]
	s_add_i32 s54, s16, 5
	s_cmp_ge_i32 s54, s52
	s_cselect_b64 s[74:75], -1, 0
	s_cmp_lt_i32 s54, s50
	s_cselect_b64 s[78:79], -1, 0
	s_and_b64 s[82:83], s[74:75], s[78:79]
	s_lshl_b64 s[84:85], s[16:17], 10
	s_lshl_b64 s[86:87], s[8:9], 10
	s_lshl_b64 s[88:89], s[10:11], 10
	s_lshl_b64 s[90:91], s[72:73], 10
	s_mov_b64 s[92:93], 0
	s_mov_b64 s[94:95], s[24:25]
	s_branch .LBB0_424
	s_nop 0
	s_nop 0
	s_nop 0
	s_nop 0
	s_nop 0
	s_nop 0
	s_nop 0
	s_nop 0
.LBB0_423:
	s_add_u32 s92, s92, 0x800
	s_addc_u32 s93, s93, 0
	s_add_u32 s26, s26, 0x400
	s_addc_u32 s27, s27, 0
	s_add_u32 s28, s28, 0x400
	s_addc_u32 s29, s29, 0
	s_add_u32 s94, s94, 0x400
	s_addc_u32 s95, s95, 0
	s_add_u32 s30, s30, 0x400
	s_addc_u32 s31, s31, 0
	s_add_u32 s34, s34, 0x400
	s_addc_u32 s35, s35, 0
	v_cvt_pk_bf16_f32 v8, v8, v9
	v_cvt_pk_bf16_f32 v9, v2, v3
	v_lshl_add_u64 v[2:3], v[54:55], 0, s[90:91]
	s_cmpk_eq_i32 s92, 0x1800
	v_cvt_pk_bf16_f32 v10, v4, v5
	v_cvt_pk_bf16_f32 v11, v6, v7
	global_store_dwordx4 v[2:3], v[8:11], off
	s_cbranch_scc1 .LBB0_448
